# attention unit: V^T tile loads and output stores widened to dwordx4 with v_permlane32_swap pairs (docs 7.3), NaN-canonicalising v_max removed; on top of last-layer halfround
# speedup vs baseline: 1.0436x; 1.0048x over previous
.LBB0_466:
	v_mov_b32_e32 v89, v87
	v_readlane_b32 s42, v254, 59
	v_lshlrev_b64 v[32:33], 11, v[88:89]
	v_readlane_b32 s43, v254, 60
	s_mov_b32 s49, s27
	v_mov_b32_e32 v85, v145
	v_lshl_add_u64 v[32:33], s[42:43], 0, v[32:33]
	v_lshl_add_u64 v[32:33], v[32:33], 0, s[48:49]
	v_lshl_add_u64 v[32:33], v[32:33], 0, v[84:85]
	v_lshl_add_u64 v[32:33], v[32:33], 0, v[84:85]
	v_cvt_pk_bf16_f32 v100, v0, v1
	v_cvt_pk_bf16_f32 v101, v2, v3
	v_cvt_pk_bf16_f32 v102, v4, v5
	v_cvt_pk_bf16_f32 v103, v6, v7
	v_readlane_b32 s26, v253, 20
	v_cvt_pk_bf16_f32 v104, v8, v9
	v_cvt_pk_bf16_f32 v105, v10, v11
	v_cvt_pk_bf16_f32 v106, v12, v13
	v_cvt_pk_bf16_f32 v107, v14, v15
	v_cvt_pk_bf16_f32 v108, v16, v17
	v_cvt_pk_bf16_f32 v109, v18, v19
	v_cvt_pk_bf16_f32 v110, v20, v21
	v_cvt_pk_bf16_f32 v111, v22, v23
	v_cvt_pk_bf16_f32 v112, v24, v25
	v_cvt_pk_bf16_f32 v113, v26, v27
	v_cvt_pk_bf16_f32 v114, v28, v29
	v_cvt_pk_bf16_f32 v115, v30, v31
	s_add_i32 s40, s40, s26
	s_sub_i32 s41, s41, s64
	s_nop 1
	v_permlane32_swap_b32 v100, v102
	v_permlane32_swap_b32 v101, v103
	v_permlane32_swap_b32 v104, v106
	v_permlane32_swap_b32 v105, v107
	v_permlane32_swap_b32 v108, v110
	v_permlane32_swap_b32 v109, v111
	v_permlane32_swap_b32 v112, v114
	v_permlane32_swap_b32 v113, v115
	s_cmpk_gt_i32 s40, 0x7ff
	global_store_dwordx4 v[32:33], v[100:103], off offset:1536
	global_store_dwordx4 v[32:33], v[104:107], off offset:1568
	global_store_dwordx4 v[32:33], v[108:111], off offset:1600
	global_store_dwordx4 v[32:33], v[112:115], off offset:1632
	s_cbranch_scc1 .LBB0_470
.LBB0_467:
	s_ashr_i32 s60, s40, 8
	s_ashr_i32 s61, s60, 31
	s_and_b32 s47, s40, 63
	s_lshl_b64 s[42:43], s[60:61], 11
	v_readlane_b32 s48, v254, 50
	s_xor_b32 s46, s47, 63
	v_or_b32_e32 v86, s42, v80
	v_readlane_b32 s49, v254, 51
	v_lshl_or_b32 v88, s46, 5, v86
	s_and_b32 s26, s40, 0xc0
	v_mov_b64_e32 v[0:1], s[48:49]
	v_mad_u64_u32 v[0:1], s[48:49], v88, s2, v[0:1]
	v_mov_b32_e32 v2, 0x3000
	v_mad_i32_i24 v1, s43, v2, v1
	s_lshl_b32 s48, s26, 1
	s_mov_b32 s49, s27
	v_lshl_add_u64 v[0:1], v[0:1], 0, s[48:49]
	v_lshl_add_u64 v[4:5], v[0:1], 0, v[144:145]
	global_load_dwordx4 v[0:3], v[4:5], off offset:3072
	global_load_dwordx4 v[48:51], v[4:5], off offset:2560
	global_load_dwordx4 v[16:19], v[4:5], off offset:3104
	global_load_dwordx4 v[52:55], v[4:5], off offset:2592
	global_load_dwordx4 v[20:23], v[4:5], off offset:3136
	global_load_dwordx4 v[56:59], v[4:5], off offset:2624
	global_load_dwordx4 v[24:27], v[4:5], off offset:3168
	global_load_dwordx4 v[60:63], v[4:5], off offset:2656
	s_lshl_b64 s[60:61], s[60:61], 12
	v_readlane_b32 s90, v254, 52
	v_or_b32_e32 v28, s26, v80
	v_readlane_b32 s91, v254, 53
	s_add_u32 s60, s90, s60
	v_mov_b32_e32 v29, v145
	v_lshlrev_b32_e32 v28, 15, v28
	s_addc_u32 s61, s91, s61
	v_mov_b32_e32 v85, v145
	s_lshl_b32 s26, s46, 6
	s_waitcnt vmcnt(0)
	v_mfma_f32_32x32x16_bf16 v[0:15], v[0:3], v[48:51], 0
	v_mfma_f32_32x32x16_bf16 v[0:15], v[16:19], v[52:55], v[0:15]
	v_lshl_add_u64 v[16:17], s[60:61], 0, v[28:29]
	v_lshl_add_u64 v[90:91], v[16:17], 0, v[84:85]
	v_lshl_add_u64 v[90:91], v[90:91], 0, v[84:85]
	v_lshl_add_u64 v[28:29], v[90:91], 0, s[26:27]
	s_mov_b32 s26, 0x100000
	global_load_dwordx4 v[16:19], v[28:29], off
	global_load_dwordx4 v[32:35], v[28:29], off offset:32
	v_add_co_u32_e32 v28, vcc, s26, v28
	v_mfma_f32_32x32x16_bf16 v[0:15], v[20:23], v[56:59], v[0:15]
	s_nop 0
	v_addc_co_u32_e32 v29, vcc, 0, v29, vcc
	global_load_dwordx4 v[20:23], v[28:29], off
	global_load_dwordx4 v[36:39], v[28:29], off offset:32
	v_mfma_f32_32x32x16_bf16 v[0:15], v[24:27], v[60:63], v[0:15]
	s_nop 11
	v_max_f32_e32 v0, 0xc2a00000, v0
	v_max_f32_e32 v2, 0xc2a00000, v2
	v_max_f32_e32 v3, 0xc2a00000, v3
	v_max_f32_e32 v4, 0xc2a00000, v4
	v_max_f32_e32 v7, 0xc2a00000, v7
	v_mul_f32_e32 v0, 0xbfb8aa3b, v0
	v_mul_f32_e32 v2, 0xbfb8aa3b, v2
	v_mul_f32_e32 v3, 0xbfb8aa3b, v3
	v_mul_f32_e32 v4, 0xbfb8aa3b, v4
	v_mul_f32_e32 v7, 0xbfb8aa3b, v7
	v_exp_f32_e32 v0, v0
	v_exp_f32_e32 v2, v2
	v_exp_f32_e32 v25, v3
	v_exp_f32_e32 v4, v4
	v_exp_f32_e32 v27, v7
	v_max_f32_e32 v5, 0xc2a00000, v5
	v_max_f32_e32 v9, 0xc2a00000, v9
	v_max_f32_e32 v10, 0xc2a00000, v10
	v_mul_f32_e32 v5, 0xbfb8aa3b, v5
	v_mul_f32_e32 v9, 0xbfb8aa3b, v9
	v_mul_f32_e32 v10, 0xbfb8aa3b, v10
	v_add_f32_e32 v7, 1.0, v0
	v_exp_f32_e32 v26, v5
	v_exp_f32_e32 v3, v9
	v_exp_f32_e32 v5, v10
	v_add_f32_e32 v9, 1.0, v2
	v_add_f32_e32 v10, 1.0, v25
	v_add_f32_e32 v28, 1.0, v4
	v_add_f32_e32 v31, 1.0, v27
	v_rcp_f32_e32 v42, v7
	v_rcp_f32_e32 v43, v9
	v_rcp_f32_e32 v10, v10
	v_rcp_f32_e32 v28, v28
	v_rcp_f32_e32 v31, v31
	v_mul_f32_e32 v0, v0, v42
	v_cndmask_b32_e64 v47, 0, v43, s[10:11]
	v_mul_f32_e32 v2, v2, v43
	v_cndmask_b32_e64 v43, 0, v10, s[12:13]
	v_mul_f32_e32 v10, v25, v10
	v_cndmask_b32_e64 v64, 0, v28, s[14:15]
	v_mul_f32_e32 v4, v4, v28
	v_mul_f32_e32 v25, v27, v31
	v_cndmask_b32_e64 v28, 1.0, v0, s[6:7]
	v_add_f32_e32 v0, 1.0, v5
	v_cndmask_b32_e64 v73, 1.0, v25, s[20:21]
	v_rcp_f32_e32 v25, v0
	v_max_f32_e32 v0, v11, v11
	v_max_f32_e32 v0, 0xc2a00000, v0
	v_mul_f32_e32 v0, 0xbfb8aa3b, v0
	v_exp_f32_e32 v11, v0
	v_max_f32_e32 v1, 0xc2a00000, v1
	v_max_f32_e32 v6, 0xc2a00000, v6
	v_mul_f32_e32 v1, 0xbfb8aa3b, v1
	v_mul_f32_e32 v6, 0xbfb8aa3b, v6
	v_exp_f32_e32 v24, v1
	v_exp_f32_e32 v6, v6
	v_add_f32_e32 v0, 1.0, v11
	v_max_f32_e32 v8, 0xc2a00000, v8
	v_rcp_f32_e32 v27, v0
	v_max_f32_e32 v0, v12, v12
	v_mul_f32_e32 v8, 0xbfb8aa3b, v8
	v_max_f32_e32 v0, 0xc2a00000, v0
	v_exp_f32_e32 v1, v8
	v_add_f32_e32 v8, 1.0, v24
	v_add_f32_e32 v29, 1.0, v26
	v_add_f32_e32 v30, 1.0, v6
	v_mul_f32_e32 v0, 0xbfb8aa3b, v0
	v_rcp_f32_e32 v8, v8
	v_rcp_f32_e32 v29, v29
	v_rcp_f32_e32 v30, v30
	v_exp_f32_e32 v0, v0
	v_cndmask_b32_e64 v46, 0, v42, s[6:7]
	v_cndmask_b32_e64 v42, 0, v8, s[8:9]
	v_mul_f32_e32 v8, v24, v8
	v_cndmask_b32_e64 v65, 0, v29, s[16:17]
	v_mul_f32_e32 v24, v26, v29
	v_mul_f32_e32 v6, v6, v30
	v_cndmask_b32_e64 v69, 1.0, v2, s[10:11]
	v_cndmask_b32_e64 v29, 1.0, v4, s[14:15]
	v_max_f32_e32 v2, v13, v13
	v_add_f32_e32 v4, 1.0, v0
	v_cndmask_b32_e64 v72, 1.0, v6, s[18:19]
	v_max_f32_e32 v2, 0xc2a00000, v2
	v_rcp_f32_e32 v6, v4
	v_max_f32_e32 v4, v14, v14
	v_cndmask_b32_e64 v70, 1.0, v10, s[12:13]
	v_mul_f32_e32 v2, 0xbfb8aa3b, v2
	v_max_f32_e32 v4, 0xc2a00000, v4
	v_max_f32_e32 v10, v15, v15
	v_exp_f32_e32 v2, v2
	v_mul_f32_e32 v4, 0xbfb8aa3b, v4
	v_max_f32_e32 v10, 0xc2a00000, v10
	v_exp_f32_e32 v4, v4
	v_mul_f32_e32 v10, 0xbfb8aa3b, v10
	v_exp_f32_e32 v10, v10
	v_add_f32_e32 v41, 1.0, v3
	v_cndmask_b32_e64 v68, 1.0, v8, s[8:9]
	v_add_f32_e32 v8, 1.0, v2
	v_rcp_f32_e32 v9, v41
	v_rcp_f32_e32 v8, v8
	v_add_f32_e32 v12, 1.0, v4
	v_add_f32_e32 v40, 1.0, v1
	v_cndmask_b32_e64 v71, 1.0, v24, s[16:17]
	v_rcp_f32_e32 v24, v12
	v_add_f32_e32 v12, 1.0, v10
	v_rcp_f32_e32 v7, v40
	v_rcp_f32_e32 v26, v12
	v_pk_mul_f32 v[2:3], v[2:3], v[8:9]
	v_mul_f32_e32 v12, v28, v68
	v_mul_f32_e32 v13, v69, v70
	v_cndmask_b32_e64 v41, 1.0, v3, s[0:1]
	v_cndmask_b32_e64 v40, 1.0, v2, s[28:29]
	v_pk_mul_f32 v[2:3], v[4:5], v[24:25]
	v_mul_f32_e32 v12, v12, v13
	v_mul_f32_e32 v13, v29, v71
	v_pk_mul_f32 v[0:1], v[0:1], v[6:7]
	v_cndmask_b32_e64 v29, 1.0, v3, s[30:31]
	v_cndmask_b32_e64 v28, 1.0, v2, s[34:35]
	v_pk_mul_f32 v[2:3], v[10:11], v[26:27]
	v_cndmask_b32_e64 v66, 0, v30, s[18:19]
	v_cndmask_b32_e64 v67, 0, v31, s[20:21]
	v_cndmask_b32_e64 v1, 1.0, v1, s[22:23]
	v_cndmask_b32_e64 v0, 1.0, v0, s[24:25]
	v_cndmask_b32_e64 v31, 1.0, v3, s[36:37]
	v_cndmask_b32_e64 v30, 1.0, v2, s[38:39]
	v_pk_mul_f32 v[0:1], v[0:1], v[40:41]
	v_pk_mul_f32 v[2:3], v[28:29], v[30:31]
	v_mul_f32_e32 v4, v72, v73
	v_pk_mul_f32 v[0:1], v[0:1], v[2:3]
	ds_bpermute_b32 v2, v81, v0
	ds_bpermute_b32 v3, v81, v1
	v_mul_f32_e32 v4, v13, v4
	v_cndmask_b32_e64 v78, 0, v6, s[24:25]
	ds_bpermute_b32 v6, v81, v4
	ds_bpermute_b32 v14, v81, v12
	s_waitcnt lgkmcnt(2)
	v_pk_mul_f32 v[0:1], v[0:1], v[2:3]
	v_cndmask_b32_e64 v74, 0, v7, s[22:23]
	v_cndmask_b32_e64 v89, 1.0, v2, s[4:5]
	v_mul_f32_e32 v2, v0, v3
	v_mov_b32_e32 v5, v0
	v_mov_b32_e32 v7, v1
	v_cndmask_b32_e64 v2, v0, v2, s[4:5]
	s_waitcnt lgkmcnt(1)
	v_pk_mul_f32 v[0:1], v[4:5], v[6:7]
	v_cndmask_b32_e64 v77, 0, v27, s[36:37]
	v_mov_b32_e32 v13, v0
	v_mov_b32_e32 v15, v1
	s_waitcnt lgkmcnt(0)
	v_pk_mul_f32 v[44:45], v[12:13], v[14:15]
	v_mul_f32_e32 v3, v1, v6
	v_mul_f32_e32 v0, v45, v14
	v_cndmask_b32_e64 v3, v1, v3, s[4:5]
	v_cndmask_b32_e64 v0, v45, v0, s[4:5]
	v_mul_f32_e32 v1, v43, v0
	v_mul_f32_e32 v0, v70, v0
	v_mul_f32_e32 v6, v67, v3
	v_mul_f32_e32 v3, v73, v3
	v_mul_f32_e32 v4, v47, v0
	v_mul_f32_e32 v0, v69, v0
	v_mul_f32_e32 v7, v66, v3
	v_mul_f32_e32 v3, v72, v3
	v_cndmask_b32_e64 v79, 0, v8, s[28:29]
	v_mul_f32_e32 v5, v42, v0
	v_mul_f32_e32 v0, v68, v0
	v_mul_f32_e32 v8, v65, v3
	v_mul_f32_e32 v3, v71, v3
	v_mul_f32_e32 v0, v46, v0
	v_mul_f32_e32 v3, v64, v3
	v_mul_f32_e32 v42, v77, v2
	v_mul_f32_e32 v2, v31, v2
	v_cndmask_b32_e64 v76, 0, v25, s[30:31]
	v_cndmask_b32_e64 v85, 0, v24, s[34:35]
	v_cndmask_b32_e64 v87, 0, v26, s[38:39]
	v_mul_f32_e32 v29, v29, v2
	v_cvt_pk_bf16_f32 v24, v0, v5
	v_cvt_pk_bf16_f32 v25, v4, v1
	v_cvt_pk_bf16_f32 v26, v3, v8
	v_cvt_pk_bf16_f32 v27, v7, v6
	v_cndmask_b32_e64 v75, 0, v9, s[0:1]
	v_mul_f32_e32 v43, v76, v2
	s_waitcnt vmcnt(3)
	v_permlane32_swap_b32 v16, v18
	v_permlane32_swap_b32 v17, v19
	s_nop 1
	v_mfma_f32_32x32x16_bf16 v[0:15], v[16:19], v[24:27], 0
	v_mul_f32_e32 v16, v41, v29
	v_mul_f32_e32 v41, v74, v16
	v_mul_f32_e32 v16, v89, v30
	v_mul_f32_e32 v46, v75, v29
	v_mul_f32_e32 v64, v85, v16
	v_mul_f32_e32 v65, v28, v16
	v_mul_f32_e32 v40, v40, v65
	s_waitcnt vmcnt(1)
	v_permlane32_swap_b32 v20, v22
	v_permlane32_swap_b32 v21, v23
	s_nop 1
	v_mfma_f32_32x32x16_bf16 v[16:31], v[20:23], v[24:27], 0
	v_mul_f32_e32 v47, v89, v87
	v_mul_f32_e32 v66, v79, v65
	v_mul_f32_e32 v65, v78, v40
	v_cvt_pk_bf16_f32 v40, v41, v46
	v_cvt_pk_bf16_f32 v41, v43, v42
	v_cvt_pk_bf16_f32 v42, v65, v66
	v_cvt_pk_bf16_f32 v43, v64, v47
	v_mul_f32_e32 v95, v44, v45
	v_cmp_gt_f32_e32 vcc, s81, v95
	v_permlane32_swap_b32 v32, v34
	v_permlane32_swap_b32 v33, v35
	s_nop 1
	v_mfma_f32_32x32x16_bf16 v[0:15], v[32:35], v[40:43], v[0:15]
	s_cmp_eq_u64 vcc, exec
	v_mov_b32_e32 v87, s43
	s_cselect_b64 s[42:43], -1, 0
	s_cmp_eq_u32 s47, 63
	s_cselect_b64 s[60:61], -1, 0
	s_or_b64 s[42:43], s[60:61], s[42:43]
	s_and_b64 vcc, exec, s[42:43]
	s_waitcnt vmcnt(0)
	v_permlane32_swap_b32 v36, v38
	v_permlane32_swap_b32 v37, v39
	s_nop 1
	v_mfma_f32_32x32x16_bf16 v[16:31], v[36:39], v[40:43], v[16:31]
	s_cbranch_vccnz .LBB0_466
	s_and_b32 s26, s41, 63
	s_lshl_b32 s26, s26, 5
	s_sub_i32 s26, s26, 32
	v_lshl_add_u64 v[92:93], v[82:83], 0, s[48:49]
	s_mov_b32 s49, 0x100000
.LBB0_469:
	v_lshl_add_u64 v[32:33], v[86:87], 0, s[26:27]
	v_mad_u64_u32 v[96:97], s[42:43], v32, s2, v[92:93]
	v_lshl_add_u64 v[100:101], s[26:27], 1, v[90:91]
	v_mad_i32_i24 v97, v33, s2, v97
	global_load_dwordx4 v[68:71], v[100:101], off
	global_load_dwordx4 v[64:67], v[100:101], off offset:32
	global_load_dwordx4 v[32:35], v[96:97], off offset:3072
	global_load_dwordx4 v[72:75], v[96:97], off offset:3104
	global_load_dwordx4 v[76:79], v[96:97], off offset:3136
	s_add_i32 s47, s46, -1
	global_load_dwordx4 v[96:99], v[96:97], off offset:3168
	s_waitcnt vmcnt(3)
	v_mfma_f32_32x32x16_bf16 v[32:47], v[32:35], v[48:51], 0
	s_waitcnt vmcnt(2)
	v_mfma_f32_32x32x16_bf16 v[32:47], v[72:75], v[52:55], v[32:47]
	v_add_co_u32_e32 v74, vcc, s49, v100
	s_nop 1
	v_addc_co_u32_e32 v75, vcc, 0, v101, vcc
	s_waitcnt vmcnt(1)
	v_mfma_f32_32x32x16_bf16 v[32:47], v[76:79], v[56:59], v[32:47]
	global_load_dwordx4 v[76:79], v[74:75], off
	s_nop 0
	global_load_dwordx4 v[72:75], v[74:75], off offset:32
	s_waitcnt vmcnt(2)
	v_mfma_f32_32x32x16_bf16 v[32:47], v[96:99], v[60:63], v[32:47]
	s_nop 11
	v_max_f32_e32 v40, 0xc2a00000, v40
	v_max_f32_e32 v41, 0xc2a00000, v41
	v_max_f32_e32 v42, 0xc2a00000, v42
	v_max_f32_e32 v43, 0xc2a00000, v43
	v_max_f32_e32 v44, 0xc2a00000, v44
	v_max_f32_e32 v45, 0xc2a00000, v45
	v_max_f32_e32 v46, 0xc2a00000, v46
	v_max_f32_e32 v47, 0xc2a00000, v47
	v_max_f32_e32 v32, 0xc2a00000, v32
	v_max_f32_e32 v33, 0xc2a00000, v33
	v_max_f32_e32 v34, 0xc2a00000, v34
	v_max_f32_e32 v35, 0xc2a00000, v35
	v_mul_f32_e32 v40, 0xbfb8aa3b, v40
	v_mul_f32_e32 v41, 0xbfb8aa3b, v41
	v_mul_f32_e32 v42, 0xbfb8aa3b, v42
	v_mul_f32_e32 v43, 0xbfb8aa3b, v43
	v_mul_f32_e32 v44, 0xbfb8aa3b, v44
	v_mul_f32_e32 v45, 0xbfb8aa3b, v45
	v_mul_f32_e32 v89, 0xbfb8aa3b, v46
	v_mul_f32_e32 v47, 0xbfb8aa3b, v47
	v_max_f32_e32 v37, 0xc2a00000, v37
	v_mul_f32_e32 v32, 0xbfb8aa3b, v32
	v_mul_f32_e32 v33, 0xbfb8aa3b, v33
	v_mul_f32_e32 v85, 0xbfb8aa3b, v34
	v_mul_f32_e32 v35, 0xbfb8aa3b, v35
	v_exp_f32_e32 v40, v40
	v_exp_f32_e32 v41, v41
	v_exp_f32_e32 v42, v42
	v_exp_f32_e32 v43, v43
	v_exp_f32_e32 v44, v44
	v_exp_f32_e32 v46, v45
	v_exp_f32_e32 v45, v89
	v_exp_f32_e32 v47, v47
	v_max_f32_e32 v36, 0xc2a00000, v36
	v_mul_f32_e32 v37, 0xbfb8aa3b, v37
	v_exp_f32_e32 v32, v32
	v_exp_f32_e32 v34, v33
	v_exp_f32_e32 v33, v85
	v_exp_f32_e32 v35, v35
	v_mul_f32_e32 v36, 0xbfb8aa3b, v36
	v_exp_f32_e32 v37, v37
	v_max_f32_e32 v38, 0xc2a00000, v38
	v_max_f32_e32 v39, 0xc2a00000, v39
	v_exp_f32_e32 v36, v36
	v_mul_f32_e32 v38, 0xbfb8aa3b, v38
	v_mul_f32_e32 v39, 0xbfb8aa3b, v39
	v_add_f32_e32 v105, 1.0, v40
	v_add_f32_e32 v107, 1.0, v41
	v_add_f32_e32 v108, 1.0, v42
	v_add_f32_e32 v109, 1.0, v43
	v_add_f32_e32 v110, 1.0, v44
	v_add_f32_e32 v111, 1.0, v46
	v_add_f32_e32 v113, 1.0, v45
	v_add_f32_e32 v114, 1.0, v47
	v_exp_f32_e32 v85, v38
	v_exp_f32_e32 v38, v39
	v_add_f32_e32 v39, 1.0, v32
	v_add_f32_e32 v89, 1.0, v34
	v_add_f32_e32 v94, 1.0, v33
	v_add_f32_e32 v99, 1.0, v35
	v_rcp_f32_e32 v106, v105
	v_rcp_f32_e32 v107, v107
	v_rcp_f32_e32 v108, v108
	v_rcp_f32_e32 v109, v109
	v_rcp_f32_e32 v110, v110
	v_rcp_f32_e32 v112, v111
	v_rcp_f32_e32 v111, v113
	v_rcp_f32_e32 v113, v114
	v_add_f32_e32 v101, 1.0, v37
	v_rcp_f32_e32 v96, v39
	v_rcp_f32_e32 v98, v89
	v_rcp_f32_e32 v97, v94
	v_rcp_f32_e32 v99, v99
	v_add_f32_e32 v100, 1.0, v36
	v_rcp_f32_e32 v89, v101
	v_rcp_f32_e32 v100, v100
	v_pk_mul_f32 v[40:41], v[40:41], v[106:107]
	v_pk_mul_f32 v[42:43], v[42:43], v[108:109]
	v_pk_mul_f32 v[44:45], v[44:45], v[110:111]
	v_pk_mul_f32 v[46:47], v[46:47], v[112:113]
	v_pk_mul_f32 v[32:33], v[32:33], v[96:97]
	v_pk_mul_f32 v[116:117], v[34:35], v[98:99]
	v_mov_b32_e32 v118, v97
	v_mov_b32_e32 v119, v99
	v_mov_b32_e32 v97, v98
	v_mov_b32_e32 v98, v111
	v_mov_b32_e32 v99, v113
	v_mov_b32_e32 v111, v112
	v_pk_mul_f32 v[112:113], v[40:41], v[40:41] op_sel_hi:[0,1]
	v_pk_mul_f32 v[120:121], v[42:43], v[42:43] op_sel_hi:[0,1]
	v_pk_mul_f32 v[122:123], v[44:45], v[46:47]
	v_mul_f32_e32 v114, v37, v89
	v_pk_mul_f32 v[122:123], v[122:123], v[122:123] op_sel:[0,1] op_sel_hi:[1,0]
	v_mov_b32_e32 v37, v113
	v_mov_b32_e32 v101, v121
	v_add_f32_e32 v102, 1.0, v85
	v_add_f32_e32 v103, 1.0, v38
	ds_bpermute_b32 v105, v81, v122
	v_pk_mul_f32 v[36:37], v[36:37], v[100:101]
	v_rcp_f32_e32 v102, v102
	v_rcp_f32_e32 v104, v103
	ds_bpermute_b32 v115, v81, v37
	v_mov_b32_e32 v39, v122
	v_mul_f32_e32 v94, v85, v102
	s_waitcnt lgkmcnt(1)
	v_pk_mul_f32 v[38:39], v[38:39], v[104:105]
	v_pk_mul_f32 v[34:35], v[32:33], v[116:117]
	v_pk_mul_f32 v[120:121], v[94:95], v[38:39]
	s_waitcnt lgkmcnt(0)
	v_pk_mul_f32 v[36:37], v[36:37], v[114:115]
	v_mov_b32_e32 v112, v35
	v_pk_mul_f32 v[36:37], v[36:37], v[120:121]
	ds_bpermute_b32 v113, v81, v36
	v_mul_f32_e32 v32, v95, v105
	v_mov_b32_e32 v35, v36
	v_cndmask_b32_e64 v105, v95, v32, s[4:5]
	v_mov_b32_e32 v103, v104
	s_waitcnt lgkmcnt(0)
	v_mul_f32_e32 v32, v37, v113
	v_pk_mul_f32 v[112:113], v[34:35], v[112:113]
	ds_bpermute_b32 v36, v81, v112
	v_cndmask_b32_e64 v35, v37, v32, s[4:5]
	v_mul_f32_e32 v34, v38, v35
	v_mul_f32_e32 v95, v94, v34
	v_mov_b32_e32 v101, v89
	v_pk_mul_f32 v[38:39], v[102:103], v[34:35]
	v_mul_f32_e32 v94, v114, v95
	v_cvt_pk_bf16_f32 v35, v38, v39
	v_pk_mul_f32 v[38:39], v[100:101], v[94:95]
	s_waitcnt lgkmcnt(0)
	v_pk_mul_f32 v[94:95], v[112:113], v[36:37]
	v_cvt_pk_bf16_f32 v34, v38, v39
	v_mul_f32_e32 v32, v95, v36
	v_cndmask_b32_e64 v37, v95, v32, s[4:5]
	v_mul_f32_e32 v36, v117, v37
	v_pk_mul_f32 v[38:39], v[118:119], v[36:37]
	v_mul_f32_e32 v37, v33, v36
	v_mul_f32_e32 v36, v116, v37
	v_pk_mul_f32 v[36:37], v[96:97], v[36:37]
	v_cvt_pk_bf16_f32 v33, v38, v39
	v_cvt_pk_bf16_f32 v32, v36, v37
	v_mul_f32_e32 v40, v121, v115
	v_cndmask_b32_e64 v39, v121, v40, s[4:5]
	v_permlane32_swap_b32 v68, v70
	v_permlane32_swap_b32 v69, v71
	s_nop 1
	v_mfma_f32_32x32x16_bf16 v[0:15], v[68:71], v[32:35], v[0:15]
	v_mul_f32_e32 v104, v105, v47
	v_mul_f32_e32 v38, v43, v39
	v_mul_f32_e32 v45, v45, v104
	v_mul_f32_e32 v44, v46, v45
	v_mul_f32_e64 v36, v98, v104
	v_mul_f32_e64 v37, v99, v105
	v_pk_mul_f32 v[46:47], v[108:109], v[38:39]
	v_cvt_pk_bf16_f32 v37, v36, v37
	s_waitcnt vmcnt(1)
	v_permlane32_swap_b32 v76, v78
	v_permlane32_swap_b32 v77, v79
	s_nop 1
	v_mfma_f32_32x32x16_bf16 v[16:31], v[76:79], v[32:35], v[16:31]
	v_mul_f32_e32 v33, v42, v38
	v_mul_f32_e32 v32, v41, v33
	v_mul_f32_e64 v38, v110, v44
	v_mul_f32_e64 v39, v111, v45
	v_mul_f32_e64 v32, v106, v32
	v_mul_f32_e64 v33, v107, v33
	v_cvt_pk_bf16_f32 v35, v46, v47
	v_cvt_pk_bf16_f32 v36, v38, v39
	v_cvt_pk_bf16_f32 v34, v32, v33
	v_mul_f32_e32 v95, v94, v95
	v_cmp_gt_f32_e32 vcc, s81, v95
	v_permlane32_swap_b32 v64, v66
	v_permlane32_swap_b32 v65, v67
	s_nop 1
	v_mfma_f32_32x32x16_bf16 v[0:15], v[64:67], v[34:37], v[0:15]
	s_cmp_lg_u64 vcc, exec
	s_cselect_b64 s[42:43], -1, 0
	s_cmp_gt_u32 s46, 1
	s_cselect_b64 s[60:61], -1, 0
	s_and_b64 s[42:43], s[42:43], s[60:61]
	s_mov_b32 s46, s47
	s_sub_i32 s26, s26, 32
	s_waitcnt vmcnt(0)
	v_permlane32_swap_b32 v72, v74
	v_permlane32_swap_b32 v73, v75
	s_nop 1
	v_mfma_f32_32x32x16_bf16 v[16:31], v[72:75], v[34:37], v[16:31]
	s_and_b64 vcc, exec, s[42:43]
	s_cbranch_vccnz .LBB0_469
	s_branch .LBB0_466
